# grid-barrier poll loops without s_sleep (tight polling), on top of the no-flips build
# baseline (speedup 1.0000x reference)
.LBB0_2160:
	v_readlane_b32 s2, v252, 26
	v_readlane_b32 s3, v252, 27
	s_mov_b64 s[26:27], -1
	s_mov_b64 s[30:31], -1
	s_nop 2
	global_load_dword v0, v1, s[2:3] sc1
	v_readlane_b32 s2, v252, 28
	v_readlane_b32 s3, v252, 29
	s_waitcnt lgkmcnt(0)
	s_nop 3
	global_load_dword v2, v1, s[2:3] sc1
	v_readlane_b32 s2, v252, 30
	v_readlane_b32 s3, v252, 31
	s_nop 1
	s_nop 2
	global_load_dword v3, v1, s[2:3] sc1
	v_readlane_b32 s2, v252, 32
	v_readlane_b32 s3, v252, 33
	s_nop 1
	s_nop 2
	global_load_dword v4, v1, s[2:3] sc1
	v_readlane_b32 s2, v252, 34
	v_readlane_b32 s3, v252, 35
	s_nop 1
	s_nop 2
	global_load_dword v5, v1, s[2:3] sc1
	v_readlane_b32 s2, v252, 36
	v_readlane_b32 s3, v252, 37
	s_nop 1
	s_nop 2
	global_load_dword v6, v1, s[2:3] sc1
	v_readlane_b32 s2, v252, 38
	v_readlane_b32 s3, v252, 39
	s_nop 1
	s_nop 2
	global_load_dword v7, v1, s[2:3] sc1
	v_readlane_b32 s2, v252, 40
	v_readlane_b32 s3, v252, 41
	s_nop 1
	s_nop 2
	global_load_dword v8, v1, s[2:3] sc1
	v_readlane_b32 s2, v252, 42
	v_readlane_b32 s3, v252, 43
	s_nop 1
	s_nop 2
	global_load_dword v9, v1, s[2:3] sc1
	v_readlane_b32 s2, v252, 44
	v_readlane_b32 s3, v252, 45
	s_nop 1
	s_nop 2
	global_load_dword v10, v1, s[2:3] sc1
	v_readlane_b32 s2, v252, 46
	v_readlane_b32 s3, v252, 47
	s_nop 1
	s_nop 2
	global_load_dword v11, v1, s[2:3] sc1
	v_readlane_b32 s2, v252, 48
	v_readlane_b32 s3, v252, 49
	s_nop 1
	s_nop 2
	global_load_dword v12, v1, s[2:3] sc1
	v_readlane_b32 s2, v252, 50
	v_readlane_b32 s3, v252, 51
	s_nop 1
	s_nop 2
	global_load_dword v13, v1, s[2:3] sc1
	v_readlane_b32 s2, v252, 52
	v_readlane_b32 s3, v252, 53
	s_nop 1
	s_nop 2
	global_load_dword v14, v1, s[2:3] sc1
	v_readlane_b32 s2, v252, 54
	v_readlane_b32 s3, v252, 55
	s_nop 1
	s_nop 2
	global_load_dword v15, v1, s[2:3] sc1
	v_readlane_b32 s2, v252, 56
	v_readlane_b32 s3, v252, 57
	s_nop 1
	s_nop 2
	global_load_dword v16, v1, s[2:3] sc1
	v_readlane_b32 s2, v250, 0
	s_waitcnt vmcnt(0)
	v_add_u32_e32 v17, v2, v0
	v_add_u32_e32 v17, v17, v3
	v_add_u32_e32 v17, v17, v4
	v_add_u32_e32 v17, v17, v5
	v_add_u32_e32 v17, v17, v6
	v_add_u32_e32 v17, v17, v7
	v_add_u32_e32 v17, v17, v8
	v_add_u32_e32 v17, v17, v9
	v_add_u32_e32 v17, v17, v10
	v_add_u32_e32 v17, v17, v11
	v_add_u32_e32 v17, v17, v12
	v_add_u32_e32 v17, v17, v13
	v_add_u32_e32 v17, v17, v14
	v_add_u32_e32 v17, v17, v15
	v_add_u32_e32 v17, v17, v16
	v_cmp_eq_u32_e32 vcc, s2, v17
	s_cbranch_vccnz .LBB0_2159
	s_and_b32 s2, s33, 0xff
	s_cmp_eq_u32 s2, 0
	s_mov_b64 s[34:35], -1
	s_nop 0
	s_cbranch_scc1 .LBB0_2164
	s_and_b64 vcc, exec, s[34:35]
	s_cbranch_vccz .LBB0_2159

.LBB0_2178:
	s_and_b32 s2, s33, 0xff
	s_mov_b64 s[42:43], -1
	s_cmp_lg_u32 s2, 0
	s_mov_b64 s[46:47], -1
	s_nop 0
	s_cbranch_scc0 .LBB0_2181
	s_and_b64 vcc, exec, s[46:47]
	s_cbranch_vccz .LBB0_2177
